# adds: adaLN staging with 24 loads in flight; MLA K/V fragment reads software-pipelined; softmax row-max tree via v_max3 chains
# speedup vs baseline: 1.6922x; 1.0105x over previous
; __device__ __forceinline__ float siluf(float x) { return x * __builtin_amdgcn_rcpf(1.f + __expf(-x)); }
; __device__ __forceinline__ void prep_phase(const Args& a, LAS unsigned char* lds) {
;     ...
;         for (int kc = 0; kc < 4; ++kc) {
;             __syncthreads();
;             for (int idx = tid; idx < 48 * 256; idx += NTHREADS) { const int s = idx >> 8, k = idx & 255;
;                 const float c = s < 32 ? a.in[2][s * 1024 + kc * 256 + k] : a.in[3][(s - 32) * 1024 + kc * 256 + k];
;                 cs[k * 48 + s] = siluf(c); }
;             __syncthreads();
.LBB0_7:
	s_barrier
	s_load_dwordx4 s[40:43], s[0:1], 0x10
	v_lshrrev_b32_e32 v8, 8, v2
	s_lshl_b32 s2, s15, 8
	v_lshl_add_u32 v9, v8, 2, v13
	v_lshl_or_b32 v8, v8, 10, v11
	v_add_u32_e32 v8, s2, v8
	v_lshlrev_b32_e32 v8, 2, v8
	s_waitcnt lgkmcnt(0)
	global_load_dword v128, v8, s[40:41]
	s_add_u32 s40, s40, 0x2000
	s_addc_u32 s41, s41, 0
	global_load_dword v129, v8, s[40:41]
	s_add_u32 s40, s40, 0x2000
	s_addc_u32 s41, s41, 0
	global_load_dword v130, v8, s[40:41]
	s_add_u32 s40, s40, 0x2000
	s_addc_u32 s41, s41, 0
	global_load_dword v131, v8, s[40:41]
	s_add_u32 s40, s40, 0x2000
	s_addc_u32 s41, s41, 0
	global_load_dword v132, v8, s[40:41]
	s_add_u32 s40, s40, 0x2000
	s_addc_u32 s41, s41, 0
	global_load_dword v133, v8, s[40:41]
	s_add_u32 s40, s40, 0x2000
	s_addc_u32 s41, s41, 0
	global_load_dword v134, v8, s[40:41]
	s_add_u32 s40, s40, 0x2000
	s_addc_u32 s41, s41, 0
	global_load_dword v135, v8, s[40:41]
	s_add_u32 s40, s40, 0x2000
	s_addc_u32 s41, s41, 0
	global_load_dword v136, v8, s[40:41]
	s_add_u32 s40, s40, 0x2000
	s_addc_u32 s41, s41, 0
	global_load_dword v137, v8, s[40:41]
	s_add_u32 s40, s40, 0x2000
	s_addc_u32 s41, s41, 0
	global_load_dword v138, v8, s[40:41]
	s_add_u32 s40, s40, 0x2000
	s_addc_u32 s41, s41, 0
	global_load_dword v139, v8, s[40:41]
	s_add_u32 s40, s40, 0x2000
	s_addc_u32 s41, s41, 0
	global_load_dword v140, v8, s[40:41]
	s_add_u32 s40, s40, 0x2000
	s_addc_u32 s41, s41, 0
	global_load_dword v141, v8, s[40:41]
	s_add_u32 s40, s40, 0x2000
	s_addc_u32 s41, s41, 0
	global_load_dword v142, v8, s[40:41]
	s_add_u32 s40, s40, 0x2000
	s_addc_u32 s41, s41, 0
	global_load_dword v143, v8, s[40:41]
	s_mov_b32 s40, s42
	s_mov_b32 s41, s43
	global_load_dword v144, v8, s[40:41]
	s_add_u32 s40, s40, 0x2000
	s_addc_u32 s41, s41, 0
	global_load_dword v145, v8, s[40:41]
	s_add_u32 s40, s40, 0x2000
	s_addc_u32 s41, s41, 0
	global_load_dword v146, v8, s[40:41]
	s_add_u32 s40, s40, 0x2000
	s_addc_u32 s41, s41, 0
	global_load_dword v147, v8, s[40:41]
	s_add_u32 s40, s40, 0x2000
	s_addc_u32 s41, s41, 0
	global_load_dword v148, v8, s[40:41]
	s_add_u32 s40, s40, 0x2000
	s_addc_u32 s41, s41, 0
	global_load_dword v149, v8, s[40:41]
	s_add_u32 s40, s40, 0x2000
	s_addc_u32 s41, s41, 0
	global_load_dword v150, v8, s[40:41]
	s_add_u32 s40, s40, 0x2000
	s_addc_u32 s41, s41, 0
	global_load_dword v151, v8, s[40:41]
	s_waitcnt vmcnt(16)
	v_mul_f32_e32 v152, 0xbfb8aa3b, v128
	v_mul_f32_e32 v153, 0xbfb8aa3b, v129
	v_mul_f32_e32 v154, 0xbfb8aa3b, v130
	v_mul_f32_e32 v155, 0xbfb8aa3b, v131
	v_mul_f32_e32 v156, 0xbfb8aa3b, v132
	v_mul_f32_e32 v157, 0xbfb8aa3b, v133
	v_mul_f32_e32 v158, 0xbfb8aa3b, v134
	v_mul_f32_e32 v159, 0xbfb8aa3b, v135
	v_exp_f32_e32 v152, v152
	v_exp_f32_e32 v153, v153
	v_exp_f32_e32 v154, v154
	v_exp_f32_e32 v155, v155
	v_exp_f32_e32 v156, v156
	v_exp_f32_e32 v157, v157
	v_exp_f32_e32 v158, v158
	v_exp_f32_e32 v159, v159
	v_add_f32_e32 v152, 1.0, v152
	v_add_f32_e32 v153, 1.0, v153
	v_add_f32_e32 v154, 1.0, v154
	v_add_f32_e32 v155, 1.0, v155
	v_add_f32_e32 v156, 1.0, v156
	v_add_f32_e32 v157, 1.0, v157
	v_add_f32_e32 v158, 1.0, v158
	v_add_f32_e32 v159, 1.0, v159
	v_rcp_f32_e32 v152, v152
	v_rcp_f32_e32 v153, v153
	v_rcp_f32_e32 v154, v154
	v_rcp_f32_e32 v155, v155
	v_rcp_f32_e32 v156, v156
	v_rcp_f32_e32 v157, v157
	v_rcp_f32_e32 v158, v158
	v_rcp_f32_e32 v159, v159
	v_mul_f32_e32 v128, v128, v152
	v_mul_f32_e32 v129, v129, v153
	v_mul_f32_e32 v130, v130, v154
	v_mul_f32_e32 v131, v131, v155
	v_mul_f32_e32 v132, v132, v156
	v_mul_f32_e32 v133, v133, v157
	v_mul_f32_e32 v134, v134, v158
	v_mul_f32_e32 v135, v135, v159
	ds_write_b32 v9, v128
	ds_write_b32 v9, v129 offset:8
	ds_write_b32 v9, v130 offset:16
	ds_write_b32 v9, v131 offset:24
	ds_write_b32 v9, v132 offset:32
	ds_write_b32 v9, v133 offset:40
	ds_write_b32 v9, v134 offset:48
	ds_write_b32 v9, v135 offset:56
	s_waitcnt vmcnt(8)
	v_mul_f32_e32 v160, 0xbfb8aa3b, v136
	v_mul_f32_e32 v161, 0xbfb8aa3b, v137
	v_mul_f32_e32 v162, 0xbfb8aa3b, v138
	v_mul_f32_e32 v163, 0xbfb8aa3b, v139
	v_mul_f32_e32 v164, 0xbfb8aa3b, v140
	v_mul_f32_e32 v165, 0xbfb8aa3b, v141
	v_mul_f32_e32 v166, 0xbfb8aa3b, v142
	v_mul_f32_e32 v167, 0xbfb8aa3b, v143
	v_exp_f32_e32 v160, v160
	v_exp_f32_e32 v161, v161
	v_exp_f32_e32 v162, v162
	v_exp_f32_e32 v163, v163
	v_exp_f32_e32 v164, v164
	v_exp_f32_e32 v165, v165
	v_exp_f32_e32 v166, v166
	v_exp_f32_e32 v167, v167
	v_add_f32_e32 v160, 1.0, v160
	v_add_f32_e32 v161, 1.0, v161
	v_add_f32_e32 v162, 1.0, v162
	v_add_f32_e32 v163, 1.0, v163
	v_add_f32_e32 v164, 1.0, v164
	v_add_f32_e32 v165, 1.0, v165
	v_add_f32_e32 v166, 1.0, v166
	v_add_f32_e32 v167, 1.0, v167
	v_rcp_f32_e32 v160, v160
	v_rcp_f32_e32 v161, v161
	v_rcp_f32_e32 v162, v162
	v_rcp_f32_e32 v163, v163
	v_rcp_f32_e32 v164, v164
	v_rcp_f32_e32 v165, v165
	v_rcp_f32_e32 v166, v166
	v_rcp_f32_e32 v167, v167
	v_mul_f32_e32 v136, v136, v160
	v_mul_f32_e32 v137, v137, v161
	v_mul_f32_e32 v138, v138, v162
	v_mul_f32_e32 v139, v139, v163
	v_mul_f32_e32 v140, v140, v164
	v_mul_f32_e32 v141, v141, v165
	v_mul_f32_e32 v142, v142, v166
	v_mul_f32_e32 v143, v143, v167
	ds_write_b32 v9, v136 offset:64
	ds_write_b32 v9, v137 offset:72
	ds_write_b32 v9, v138 offset:80
	ds_write_b32 v9, v139 offset:88
	ds_write_b32 v9, v140 offset:96
	ds_write_b32 v9, v141 offset:104
	ds_write_b32 v9, v142 offset:112
	ds_write_b32 v9, v143 offset:120
	s_waitcnt vmcnt(0)
	v_mul_f32_e32 v168, 0xbfb8aa3b, v144
	v_mul_f32_e32 v169, 0xbfb8aa3b, v145
	v_mul_f32_e32 v170, 0xbfb8aa3b, v146
	v_mul_f32_e32 v171, 0xbfb8aa3b, v147
	v_mul_f32_e32 v172, 0xbfb8aa3b, v148
	v_mul_f32_e32 v173, 0xbfb8aa3b, v149
	v_mul_f32_e32 v174, 0xbfb8aa3b, v150
	v_mul_f32_e32 v175, 0xbfb8aa3b, v151
	v_exp_f32_e32 v168, v168
	v_exp_f32_e32 v169, v169
	v_exp_f32_e32 v170, v170
	v_exp_f32_e32 v171, v171
	v_exp_f32_e32 v172, v172
	v_exp_f32_e32 v173, v173
	v_exp_f32_e32 v174, v174
	v_exp_f32_e32 v175, v175
	v_add_f32_e32 v168, 1.0, v168
	v_add_f32_e32 v169, 1.0, v169
	v_add_f32_e32 v170, 1.0, v170
	v_add_f32_e32 v171, 1.0, v171
	v_add_f32_e32 v172, 1.0, v172
	v_add_f32_e32 v173, 1.0, v173
	v_add_f32_e32 v174, 1.0, v174
	v_add_f32_e32 v175, 1.0, v175
	v_rcp_f32_e32 v168, v168
	v_rcp_f32_e32 v169, v169
	v_rcp_f32_e32 v170, v170
	v_rcp_f32_e32 v171, v171
	v_rcp_f32_e32 v172, v172
	v_rcp_f32_e32 v173, v173
	v_rcp_f32_e32 v174, v174
	v_rcp_f32_e32 v175, v175
	v_mul_f32_e32 v144, v144, v168
	v_mul_f32_e32 v145, v145, v169
	v_mul_f32_e32 v146, v146, v170
	v_mul_f32_e32 v147, v147, v171
	v_mul_f32_e32 v148, v148, v172
	v_mul_f32_e32 v149, v149, v173
	v_mul_f32_e32 v150, v150, v174
	v_mul_f32_e32 v151, v151, v175
	ds_write_b32 v9, v144 offset:128
	ds_write_b32 v9, v145 offset:136
	ds_write_b32 v9, v146 offset:144
	ds_write_b32 v9, v147 offset:152
	ds_write_b32 v9, v148 offset:160
	ds_write_b32 v9, v149 offset:168
	ds_write_b32 v9, v150 offset:176
	ds_write_b32 v9, v151 offset:184
	s_mov_b32 s8, -8
	v_mov_b64_e32 v[8:9], v[4:5]
	v_mov_b32_e32 v51, v37
	s_waitcnt lgkmcnt(0)
	s_barrier

; #define LAS __attribute__((address_space(3)))
; template <bool MLA>
; __device__ __forceinline__ void attn_phase(const Args& a, LAS unsigned char* lds) {
;     ...
;             f32x4 s[2][4];
;             __builtin_amdgcn_s_setprio(1);
; #pragma unroll
;             for (int sub = 0; sub < 4; ++sub) {
;                 f32x4 a0 = (f32x4){0.f, 0.f, 0.f, 0.f}, a1 = a0;
; #pragma unroll
;                 for (int ks = 0; ks < NKS; ++ks) {
;                     const bf16x8 kf = *(const LAS bf16x8*)(Ks + (sub * 16 + r) * QST + ks * 32 + quad * 8);
;                     a0 = __builtin_amdgcn_mfma_f32_16x16x32_bf16(kf, qf[0][ks], a0, 0, 0, 0);
;                     a1 = __builtin_amdgcn_mfma_f32_16x16x32_bf16(kf, qf[1][ks], a1, 0, 0, 0);
;                 }
;                 s[0][sub] = a0; s[1][sub] = a1;
;             }
;             __builtin_amdgcn_s_setprio(0);
;             bf16x8 pf[2][2];
;             const bool need_mask = kt * 64 + 64 > nkw;
; #pragma unroll
;             for (int g = 0; g < 2; ++g) {
;                 f32x4 sv[4];
; #pragma unroll
;                 for (int sub = 0; sub < 4; ++sub) sv[sub] = s[g][sub] * scale;
;                 if (!MLA) {
; #pragma unroll
;                     for (int sub = 0; sub < 4; ++sub)
; #pragma unroll
;                         for (int jj = 0; jj < 4; ++jj) sv[sub][jj] += biasT[head * 256 + 191 + qi[g] - (kt * 64 + sub * 16 + quad * 4 + jj)];
;                 }
;                 if (need_mask) {
; #pragma unroll
;                     for (int sub = 0; sub < 4; ++sub)
; #pragma unroll
;                         for (int jj = 0; jj < 4; ++jj) if (kt * 64 + sub * 16 + quad * 4 + jj >= nkw) sv[sub][jj] = -INFINITY;
;                 }
.LBB0_497:
	s_bitcmp1_b32 s6, 0
	s_cselect_b32 s0, 0x5600, 0
	s_add_i32 s68, s0, 0
	s_setprio 1
	v_add3_u32 v0, s68, v165, v119
	ds_read_b128 v[208:211], v0 offset:53248
	ds_read_b128 v[212:215], v0 offset:53312
	ds_read_b128 v[216:219], v0 offset:53376
	ds_read_b128 v[220:223], v0 offset:56576
	ds_read_b128 v[224:227], v0 offset:56640
	ds_read_b128 v[228:231], v0 offset:56704
	s_waitcnt lgkmcnt(5)
	v_mfma_f32_16x16x32_bf16 v[134:137], v[208:211], v[24:27], 0
	v_mfma_f32_16x16x32_bf16 v[72:75], v[208:211], v[12:15], 0
	s_waitcnt lgkmcnt(4)
	v_mfma_f32_16x16x32_bf16 v[134:137], v[212:215], v[20:23], v[134:137]
	v_mfma_f32_16x16x32_bf16 v[72:75], v[212:215], v[8:11], v[72:75]
	s_waitcnt lgkmcnt(3)
	v_mfma_f32_16x16x32_bf16 v[134:137], v[216:219], v[16:19], v[134:137]
	v_mfma_f32_16x16x32_bf16 v[72:75], v[216:219], v[4:7], v[72:75]
	ds_read_b128 v[208:211], v0 offset:59904
	ds_read_b128 v[212:215], v0 offset:59968
	ds_read_b128 v[216:219], v0 offset:60032
	s_waitcnt lgkmcnt(5)
	v_mfma_f32_16x16x32_bf16 v[150:153], v[220:223], v[24:27], 0
	v_mfma_f32_16x16x32_bf16 v[76:79], v[220:223], v[12:15], 0
	s_waitcnt lgkmcnt(4)
	v_mfma_f32_16x16x32_bf16 v[150:153], v[224:227], v[20:23], v[150:153]
	v_mfma_f32_16x16x32_bf16 v[76:79], v[224:227], v[8:11], v[76:79]
	s_waitcnt lgkmcnt(3)
	v_mfma_f32_16x16x32_bf16 v[150:153], v[228:231], v[16:19], v[150:153]
	v_mfma_f32_16x16x32_bf16 v[76:79], v[228:231], v[4:7], v[76:79]
	ds_read_b128 v[220:223], v0 offset:63232
	ds_read_b128 v[224:227], v0 offset:63296
	ds_read_b128 v[228:231], v0 offset:63360
	s_waitcnt lgkmcnt(5)
	v_mfma_f32_16x16x32_bf16 v[146:149], v[208:211], v[24:27], 0
	v_mfma_f32_16x16x32_bf16 v[80:83], v[208:211], v[12:15], 0
	s_waitcnt lgkmcnt(4)
	v_mfma_f32_16x16x32_bf16 v[146:149], v[212:215], v[20:23], v[146:149]
	v_mfma_f32_16x16x32_bf16 v[80:83], v[212:215], v[8:11], v[80:83]
	s_waitcnt lgkmcnt(3)
	v_mfma_f32_16x16x32_bf16 v[146:149], v[216:219], v[16:19], v[146:149]
	v_mfma_f32_16x16x32_bf16 v[80:83], v[216:219], v[4:7], v[80:83]
	s_waitcnt lgkmcnt(2)
	v_mfma_f32_16x16x32_bf16 v[138:141], v[220:223], v[24:27], 0
	v_mfma_f32_16x16x32_bf16 v[84:87], v[220:223], v[12:15], 0
	s_waitcnt lgkmcnt(1)
	v_mfma_f32_16x16x32_bf16 v[138:141], v[224:227], v[20:23], v[138:141]
	v_mfma_f32_16x16x32_bf16 v[84:87], v[224:227], v[8:11], v[84:87]
	s_waitcnt lgkmcnt(0)
	v_mfma_f32_16x16x32_bf16 v[138:141], v[228:231], v[16:19], v[138:141]
	v_mfma_f32_16x16x32_bf16 v[84:87], v[228:231], v[4:7], v[84:87]
	s_setprio 0
	v_add_u32_e32 v2, s66, v166
	s_cmp_gt_i32 s66, s65
	v_subrev_u32_e32 v0, 64, v2
	s_mov_b32 s0, 0x3e16c740
	v_subrev_u32_e32 v176, 63, v2
	v_subrev_u32_e32 v177, 62, v2
	v_subrev_u32_e32 v178, 61, v2
	v_subrev_u32_e32 v179, 48, v2
	v_subrev_u32_e32 v180, 47, v2
	v_subrev_u32_e32 v181, 46, v2
	v_subrev_u32_e32 v182, 45, v2
	v_subrev_u32_e32 v183, 32, v2
	v_subrev_u32_e32 v184, 31, v2
	v_subrev_u32_e32 v185, 30, v2
	v_subrev_u32_e32 v197, 29, v2
	v_add_u32_e32 v202, -16, v2
	v_add_u32_e32 v203, -15, v2
	v_add_u32_e32 v204, -14, v2
	v_add_u32_e32 v205, -13, v2
	s_cselect_b64 s[58:59], -1, 0
	s_cmp_le_i32 s66, s65
	v_pk_mul_f32 v[140:141], v[140:141], s[0:1] op_sel_hi:[1,0]
	v_pk_mul_f32 v[144:145], v[148:149], s[0:1] op_sel_hi:[1,0]
	v_pk_mul_f32 v[148:149], v[152:153], s[0:1] op_sel_hi:[1,0]
	v_pk_mul_f32 v[152:153], v[136:137], s[0:1] op_sel_hi:[1,0]
	v_pk_mul_f32 v[142:143], v[138:139], s[0:1] op_sel_hi:[1,0]
	v_pk_mul_f32 v[146:147], v[146:147], s[0:1] op_sel_hi:[1,0]
	v_pk_mul_f32 v[150:151], v[150:151], s[0:1] op_sel_hi:[1,0]
	v_pk_mul_f32 v[154:155], v[134:135], s[0:1] op_sel_hi:[1,0]
	v_cmp_gt_i32_e32 vcc, s65, v0
	v_cmp_gt_i32_e64 s[0:1], s65, v176
	v_cmp_gt_i32_e64 s[2:3], s65, v177
	v_cmp_gt_i32_e64 s[4:5], s65, v178
	v_cmp_gt_i32_e64 s[6:7], s65, v179
	v_cmp_gt_i32_e64 s[10:11], s65, v180
	v_cmp_gt_i32_e64 s[12:13], s65, v181
	v_cmp_gt_i32_e64 s[14:15], s65, v182
	v_cmp_gt_i32_e64 s[16:17], s65, v183
	v_cmp_gt_i32_e64 s[18:19], s65, v184
	v_cmp_gt_i32_e64 s[20:21], s65, v185
	v_cmp_gt_i32_e64 s[22:23], s65, v197
	v_cmp_gt_i32_e64 s[24:25], s65, v202
	v_cmp_gt_i32_e64 s[26:27], s65, v203
	v_cmp_gt_i32_e64 s[28:29], s65, v204
	v_cmp_gt_i32_e64 s[8:9], s65, v205
	s_cbranch_scc1 .LBB0_499
	s_or_b64 s[28:29], s[8:9], s[28:29]
	s_or_b64 s[26:27], s[28:29], s[26:27]
	s_or_b64 s[24:25], s[26:27], s[24:25]
	s_or_b64 s[22:23], s[24:25], s[22:23]
	s_or_b64 s[20:21], s[22:23], s[20:21]
	s_or_b64 s[18:19], s[20:21], s[18:19]
	s_or_b64 s[16:17], s[18:19], s[16:17]
	s_or_b64 s[14:15], s[16:17], s[14:15]
	s_or_b64 s[12:13], s[14:15], s[12:13]
	s_or_b64 s[10:11], s[12:13], s[10:11]
	s_or_b64 s[6:7], s[10:11], s[6:7]
	s_or_b64 s[4:5], s[6:7], s[4:5]
	s_or_b64 s[2:3], s[4:5], s[2:3]
	s_or_b64 s[0:1], s[2:3], s[0:1]
	s_or_b64 vcc, s[0:1], vcc
	v_cndmask_b32_e64 v140, v245, v140, s[28:29]
	v_cndmask_b32_e64 v143, v245, v143, s[26:27]
	v_cndmask_b32_e64 v142, v245, v142, s[24:25]
	v_cndmask_b32_e64 v145, v245, v145, s[22:23]
	v_cndmask_b32_e64 v144, v245, v144, s[20:21]
	v_cndmask_b32_e64 v147, v245, v147, s[18:19]
	v_cndmask_b32_e64 v146, v245, v146, s[16:17]
	v_cndmask_b32_e64 v149, v245, v149, s[14:15]
	v_cndmask_b32_e64 v148, v245, v148, s[12:13]
	v_cndmask_b32_e64 v151, v245, v151, s[10:11]
	v_cndmask_b32_e64 v150, v245, v150, s[6:7]
	v_cndmask_b32_e64 v153, v245, v153, s[4:5]
	v_cndmask_b32_e64 v152, v245, v152, s[2:3]
	v_cndmask_b32_e64 v155, v245, v155, s[0:1]
	v_cndmask_b32_e32 v154, v245, v154, vcc
	v_cndmask_b32_e64 v141, v245, v141, s[8:9]
; __device__ __forceinline__ unsigned pk2(float lo, float hi) { const f32x2 v = {lo, hi}; const bf16v2_t b = __builtin_convertvector(v, bf16v2_t); return __builtin_bit_cast(unsigned, b); }
; template <bool MLA>
; __device__ __forceinline__ void attn_phase(const Args& a, LAS unsigned char* lds) {
;     ...
;                 if (need_mask) {
; #pragma unroll
;                     for (int sub = 0; sub < 4; ++sub)
; #pragma unroll
;                         for (int jj = 0; jj < 4; ++jj) if (kt * 64 + sub * 16 + quad * 4 + jj >= nkw) sv[sub][jj] = -INFINITY;
;                 }
;                 float mx = -INFINITY;
; #pragma unroll
;                 for (int sub = 0; sub < 4; ++sub) mx = fmaxf(fmaxf(fmaxf(mx, sv[sub][0]), fmaxf(sv[sub][1], sv[sub][2])), sv[sub][3]);
;                 mx = fmaxf(mx, __shfl_xor(mx, 16)); mx = fmaxf(mx, __shfl_xor(mx, 32));
;                 const float mn = fmaxf(m[g], mx), alpha = __builtin_amdgcn_exp2f(m[g] - mn); m[g] = mn;
;                 f32x4 ps4 = (f32x4){0.f, 0.f, 0.f, 0.f};
; #pragma unroll
;                 for (int sub = 0; sub < 4; ++sub) {
;                     const f32x4 d = sv[sub] - mn;
;                     const f32x4 pe = (f32x4){__builtin_amdgcn_exp2f(d[0]), __builtin_amdgcn_exp2f(d[1]), __builtin_amdgcn_exp2f(d[2]), __builtin_amdgcn_exp2f(d[3])};
;                     s[g][sub] = pe; ps4 += pe;
;                 }
;                 lsum[g] = lsum[g] * alpha + ((ps4[0] + ps4[1]) + (ps4[2] + ps4[3]));
; #pragma unroll
;                 for (int et = 0; et < 4; ++et) O[g][et] *= alpha;
; #pragma unroll
;                 for (int s2 = 0; s2 < 2; ++s2) {
;                     const unsigned a0 = pk2(s[g][2 * s2][0], s[g][2 * s2][1]), a1 = pk2(s[g][2 * s2][2], s[g][2 * s2][3]), a2 = pk2(s[g][2 * s2 + 1][0], s[g][2 * s2 + 1][1]), a3 = pk2(s[g][2 * s2 + 1][2], s[g][2 * s2 + 1][3]);
;                     const u32x4 pu = (u32x4){a0, a1, a2, a3}; pf[g][s2] = *(const bf16x8*)&pu;
.LBB0_499:
	v_max3_f32 v2, v152, v155, v154
	v_max3_f32 v134, v144, v147, v146
	v_max3_f32 v2, v2, v148, v151
	v_max3_f32 v134, v134, v140, v143
	v_max3_f32 v2, v2, v153, v150
	v_max3_f32 v134, v134, v145, v142
	s_mov_b32 s0, 0xff800000
	v_max_f32_e32 v2, v2, v149
	v_max3_f32 v2, v2, v134, v141
	ds_bpermute_b32 v3, v167, v2
	s_mov_b32 s0, 0x3e16c740
	v_pk_mul_f32 v[134:135], v[78:79], s[0:1] op_sel_hi:[1,0]
	v_pk_mul_f32 v[136:137], v[74:75], s[0:1] op_sel_hi:[1,0]
	v_pk_mul_f32 v[80:81], v[80:81], s[0:1] op_sel_hi:[1,0]
	s_waitcnt lgkmcnt(0)
	v_max_f32_e32 v206, v2, v3
	ds_bpermute_b32 v207, v168, v206
	v_pk_mul_f32 v[2:3], v[86:87], s[0:1] op_sel_hi:[1,0]
	v_pk_mul_f32 v[86:87], v[82:83], s[0:1] op_sel_hi:[1,0]
	v_pk_mul_f32 v[82:83], v[84:85], s[0:1] op_sel_hi:[1,0]
	v_pk_mul_f32 v[84:85], v[76:77], s[0:1] op_sel_hi:[1,0]
	s_andn2_b64 vcc, exec, s[58:59]
	v_pk_mul_f32 v[138:139], v[72:73], s[0:1] op_sel_hi:[1,0]
	s_cbranch_vccnz .LBB0_501
	v_cmp_gt_i32_e64 s[26:27], s65, v204
	v_cmp_gt_i32_e64 s[28:29], s65, v205
	v_cmp_gt_i32_e64 s[24:25], s65, v203
	s_or_b64 s[26:27], s[28:29], s[26:27]
	v_cmp_gt_i32_e64 s[22:23], s65, v202
	s_or_b64 s[24:25], s[26:27], s[24:25]
	v_cmp_gt_i32_e64 s[20:21], s65, v197
	s_or_b64 s[22:23], s[24:25], s[22:23]
	v_cmp_gt_i32_e64 s[18:19], s65, v185
	s_or_b64 s[20:21], s[22:23], s[20:21]
	v_cmp_gt_i32_e64 s[16:17], s65, v184
	s_or_b64 s[18:19], s[20:21], s[18:19]
	v_cmp_gt_i32_e64 s[14:15], s65, v183
	s_or_b64 s[16:17], s[18:19], s[16:17]
	v_cmp_gt_i32_e64 s[12:13], s65, v182
	s_or_b64 s[14:15], s[16:17], s[14:15]
	v_cmp_gt_i32_e64 s[10:11], s65, v181
	s_or_b64 s[12:13], s[14:15], s[12:13]
	v_cmp_gt_i32_e64 s[8:9], s65, v180
	s_or_b64 s[10:11], s[12:13], s[10:11]
	v_cmp_gt_i32_e64 s[6:7], s65, v179
	s_or_b64 s[8:9], s[10:11], s[8:9]
	v_cmp_gt_i32_e64 s[4:5], s65, v178
	s_or_b64 s[6:7], s[8:9], s[6:7]
	v_cmp_gt_i32_e64 s[2:3], s65, v177
	s_or_b64 s[4:5], s[6:7], s[4:5]
	v_cmp_gt_i32_e64 s[0:1], s65, v176
	s_or_b64 s[2:3], s[4:5], s[2:3]
	v_cmp_gt_i32_e32 vcc, s65, v0
	s_or_b64 s[0:1], s[2:3], s[0:1]
	s_or_b64 vcc, s[0:1], vcc
	v_cndmask_b32_e64 v3, v245, v3, s[28:29]
	v_cndmask_b32_e64 v2, v245, v2, s[26:27]
	v_cndmask_b32_e64 v83, v245, v83, s[24:25]
	v_cndmask_b32_e64 v82, v245, v82, s[22:23]
	v_cndmask_b32_e64 v87, v245, v87, s[20:21]
	v_cndmask_b32_e64 v86, v245, v86, s[18:19]
	v_cndmask_b32_e64 v81, v245, v81, s[16:17]
	v_cndmask_b32_e64 v80, v245, v80, s[14:15]
	v_cndmask_b32_e64 v135, v245, v135, s[12:13]
	v_cndmask_b32_e64 v134, v245, v134, s[10:11]
	v_cndmask_b32_e64 v85, v245, v85, s[8:9]
	v_cndmask_b32_e64 v84, v245, v84, s[6:7]
	v_cndmask_b32_e64 v137, v245, v137, s[4:5]
	v_cndmask_b32_e64 v136, v245, v136, s[2:3]
	v_cndmask_b32_e64 v139, v245, v139, s[0:1]
	v_cndmask_b32_e32 v138, v245, v138, vcc
.LBB0_501:
	s_waitcnt lgkmcnt(0)
	v_max3_f32 v0, v175, v206, v207
	v_sub_f32_e32 v74, v155, v0
	v_sub_f32_e32 v75, v154, v0
	v_sub_f32_e32 v72, v153, v0
	v_sub_f32_e32 v73, v152, v0
	v_exp_f32_e32 v152, v75
	v_exp_f32_e32 v153, v74
	v_sub_f32_e32 v78, v148, v0
	v_sub_f32_e32 v79, v151, v0
	v_sub_f32_e32 v148, v150, v0
	v_sub_f32_e32 v77, v149, v0
	v_exp_f32_e32 v148, v148
	v_exp_f32_e32 v149, v79
	v_exp_f32_e32 v150, v78
	v_sub_f32_e32 v78, v144, v0
	v_sub_f32_e32 v79, v147, v0
	v_sub_f32_e32 v144, v146, v0
	v_sub_f32_e32 v76, v175, v0
	v_exp_f32_e32 v151, v77
	v_sub_f32_e32 v77, v145, v0
	v_exp_f32_e32 v144, v144
	v_exp_f32_e32 v145, v79
	v_exp_f32_e32 v146, v78
	v_sub_f32_e32 v78, v140, v0
	v_sub_f32_e32 v79, v143, v0
	v_sub_f32_e32 v140, v142, v0
	v_exp_f32_e32 v142, v140
	v_exp_f32_e32 v143, v79
	v_exp_f32_e32 v178, v76
	v_exp_f32_e32 v154, v73
	v_exp_f32_e32 v155, v72
	v_pk_add_f32 v[72:73], v[152:153], 0 op_sel_hi:[1,0]
	v_exp_f32_e32 v147, v77
	v_pk_add_f32 v[72:73], v[148:149], v[72:73]
	v_sub_f32_e32 v77, v141, v0
	v_pk_add_f32 v[72:73], v[144:145], v[72:73]
	v_exp_f32_e32 v176, v78
	v_pk_add_f32 v[72:73], v[142:143], v[72:73]
	v_pk_mul_f32 v[78:79], v[58:59], v[178:179] op_sel_hi:[1,0]
	v_pk_mul_f32 v[58:59], v[70:71], v[178:179] op_sel_hi:[1,0]
	v_cvt_pk_bf16_f32 v70, v142, v143
	v_max3_f32 v141, v136, v139, v138
	v_max3_f32 v142, v86, v81, v80
	v_max3_f32 v141, v141, v134, v85
	v_max3_f32 v142, v142, v2, v83
	v_max3_f32 v141, v141, v137, v84
	v_max3_f32 v142, v142, v87, v82
	s_mov_b32 s0, 0xff800000
	v_max_f32_e32 v141, v141, v135
	v_max3_f32 v141, v141, v142, v3
	ds_bpermute_b32 v142, v167, v141
	v_pk_add_f32 v[74:75], v[154:155], 0 op_sel_hi:[1,0]
	v_exp_f32_e32 v177, v77
	v_pk_add_f32 v[74:75], v[150:151], v[74:75]
	v_pk_mul_f32 v[76:77], v[56:57], v[178:179] op_sel_hi:[1,0]
	s_waitcnt lgkmcnt(0)
	v_max_f32_e32 v141, v141, v142
	ds_bpermute_b32 v142, v168, v141
	v_pk_add_f32 v[74:75], v[146:147], v[74:75]
	v_pk_mul_f32 v[56:57], v[68:69], v[178:179] op_sel_hi:[1,0]
	v_cvt_pk_bf16_f32 v69, v146, v147
	v_cvt_pk_bf16_f32 v68, v144, v145
	s_waitcnt lgkmcnt(0)
; #define LAS __attribute__((address_space(3)))
; __device__ __forceinline__ unsigned pk2(float lo, float hi) { const f32x2 v = {lo, hi}; const bf16v2_t b = __builtin_convertvector(v, bf16v2_t); return __builtin_bit_cast(unsigned, b); }
; template <bool MLA>
; __device__ __forceinline__ void attn_phase(const Args& a, LAS unsigned char* lds) {
;     ...
;                 for (int sub = 0; sub < 4; ++sub) mx = fmaxf(fmaxf(fmaxf(mx, sv[sub][0]), fmaxf(sv[sub][1], sv[sub][2])), sv[sub][3]);
;                 mx = fmaxf(mx, __shfl_xor(mx, 16)); mx = fmaxf(mx, __shfl_xor(mx, 32));
;                 const float mn = fmaxf(m[g], mx), alpha = __builtin_amdgcn_exp2f(m[g] - mn); m[g] = mn;
;                 f32x4 ps4 = (f32x4){0.f, 0.f, 0.f, 0.f};
; #pragma unroll
;                 for (int sub = 0; sub < 4; ++sub) {
;                     const f32x4 d = sv[sub] - mn;
;                     const f32x4 pe = (f32x4){__builtin_amdgcn_exp2f(d[0]), __builtin_amdgcn_exp2f(d[1]), __builtin_amdgcn_exp2f(d[2]), __builtin_amdgcn_exp2f(d[3])};
;                     s[g][sub] = pe; ps4 += pe;
;                 }
;                 lsum[g] = lsum[g] * alpha + ((ps4[0] + ps4[1]) + (ps4[2] + ps4[3]));
; #pragma unroll
;                 for (int et = 0; et < 4; ++et) O[g][et] *= alpha;
; #pragma unroll
;                 for (int s2 = 0; s2 < 2; ++s2) {
;                     const unsigned a0 = pk2(s[g][2 * s2][0], s[g][2 * s2][1]), a1 = pk2(s[g][2 * s2][2], s[g][2 * s2][3]), a2 = pk2(s[g][2 * s2 + 1][0], s[g][2 * s2 + 1][1]), a3 = pk2(s[g][2 * s2 + 1][2], s[g][2 * s2 + 1][3]);
;                     const u32x4 pu = (u32x4){a0, a1, a2, a3}; pf[g][s2] = *(const bf16x8*)&pu;
;                 }
;             }
; #pragma unroll
;             for (int s2 = 0; s2 < 2; ++s2)
; #pragma unroll
;                 for (int et = 0; et < 4; ++et) {
;                     const LAS bf16_t* vp = VTs + (et * 16 + r) * 68 + s2 * 32 + quad * 4;
;                     const u32x2 v0 = *(const LAS u32x2*)vp, v1 = *(const LAS u32x2*)(vp + 16);
;                     const u32x4 vu = (u32x4){v0.x, v0.y, v1.x, v1.y};
;                     O[0][et] = __builtin_amdgcn_mfma_f32_16x16x32_bf16(*(const bf16x8*)&vu, pf[0][s2], O[0][et], 0, 0, 0);
;                     O[1][et] = __builtin_amdgcn_mfma_f32_16x16x32_bf16(*(const bf16x8*)&vu, pf[1][s2], O[1][et], 0, 0, 0);
;                 }
	v_max3_f32 v141, v173, v141, v142
	v_add3_u32 v232, s68, v118, v169
	v_add_u32_e32 v233, 0x10000, v232
	v_add_u32_e32 v239, 0x10800, v232
	v_add_u32_e32 v240, 0x11000, v232
	v_add_u32_e32 v246, 0x11800, v232
	ds_read2_b64 v[208:211], v233 offset0:128 offset1:132
	ds_read2_b64 v[212:215], v239 offset0:144 offset1:148
	ds_read2_b64 v[216:219], v240 offset0:160 offset1:164
	ds_read2_b64 v[220:223], v246 offset0:176 offset1:180
	ds_read2_b64 v[224:227], v239 offset0:152 offset1:156
	ds_read2_b64 v[228:231], v240 offset0:168 offset1:172
	v_sub_f32_e32 v142, v137, v141
	v_sub_f32_e32 v143, v136, v141
	v_sub_f32_e32 v137, v139, v141
	v_sub_f32_e32 v136, v138, v141
	v_exp_f32_e32 v138, v143
	v_exp_f32_e32 v139, v142
	v_sub_f32_e32 v147, v135, v141
	v_sub_f32_e32 v146, v134, v141
	v_exp_f32_e32 v146, v146
	v_exp_f32_e32 v147, v147
	v_exp_f32_e32 v136, v136
	v_exp_f32_e32 v137, v137
	v_sub_f32_e32 v85, v85, v141
	v_sub_f32_e32 v84, v84, v141
	v_pk_add_f32 v[144:145], v[138:139], 0 op_sel_hi:[1,0]
	v_exp_f32_e32 v134, v84
	v_exp_f32_e32 v135, v85
	v_sub_f32_e32 v81, v81, v141
	v_sub_f32_e32 v80, v80, v141
	v_pk_add_f32 v[84:85], v[146:147], v[144:145]
	v_exp_f32_e32 v144, v80
	v_exp_f32_e32 v145, v81
	v_pk_add_f32 v[74:75], v[176:177], v[74:75]
	v_pk_add_f32 v[142:143], v[136:137], 0 op_sel_hi:[1,0]
	v_sub_f32_e32 v87, v87, v141
	v_sub_f32_e32 v86, v86, v141
	v_add_f32_e32 v72, v72, v73
	v_add_f32_e32 v73, v74, v75
	v_pk_mul_f32 v[74:75], v[62:63], v[178:179] op_sel_hi:[1,0]
	v_cvt_pk_bf16_f32 v62, v148, v149
	v_pk_add_f32 v[142:143], v[134:135], v[142:143]
	v_exp_f32_e32 v148, v86
	v_exp_f32_e32 v149, v87
	v_sub_f32_e32 v86, v3, v141
	v_sub_f32_e32 v87, v2, v141
	v_sub_f32_e32 v3, v83, v141
	v_sub_f32_e32 v2, v82, v141
	v_pk_add_f32 v[80:81], v[144:145], v[142:143]
	v_exp_f32_e32 v2, v2
	v_exp_f32_e32 v3, v3
	v_exp_f32_e32 v142, v87
	v_exp_f32_e32 v143, v86
	v_cvt_pk_bf16_f32 v63, v150, v151
	v_sub_f32_e32 v150, v173, v141
	v_pk_add_f32 v[84:85], v[148:149], v[84:85]
	v_pk_add_f32 v[80:81], v[2:3], v[80:81]
	v_pk_add_f32 v[82:83], v[142:143], v[84:85]
	v_exp_f32_e32 v150, v150
	v_pk_mov_b32 v[84:85], v[80:81], v[82:83] op_sel:[1,0]
	v_mov_b32_e32 v81, v83
	v_pk_add_f32 v[80:81], v[84:85], v[80:81]
	s_add_i32 s68, s68, 0xd000
	v_add_f32_e32 v151, v80, v81
	v_fmac_f32_e32 v151, v127, v150
	v_pk_mul_f32 v[82:83], v[42:43], v[150:151] op_sel_hi:[1,0]
	v_pk_mul_f32 v[42:43], v[54:55], v[150:151] op_sel_hi:[1,0]
	v_cvt_pk_bf16_f32 v54, v2, v3
	v_add3_u32 v2, s68, v118, v169
	v_add_u32_e32 v3, 0x3000, v2
	v_pk_mul_f32 v[86:87], v[46:47], v[150:151] op_sel_hi:[1,0]
	v_pk_mul_f32 v[84:85], v[44:45], v[150:151] op_sel_hi:[1,0]
	v_cvt_pk_bf16_f32 v44, v136, v137
	v_cvt_pk_bf16_f32 v46, v134, v135
	v_add_f32_e32 v140, v72, v73
	v_pk_mul_f32 v[72:73], v[60:61], v[178:179] op_sel_hi:[1,0]
	v_cvt_pk_bf16_f32 v60, v152, v153
	v_cvt_pk_bf16_f32 v61, v154, v155
	v_pk_mul_f32 v[80:81], v[40:41], v[150:151] op_sel_hi:[1,0]
	v_cvt_pk_bf16_f32 v45, v138, v139
	v_cvt_pk_bf16_f32 v47, v146, v147
	v_add_u32_e32 v127, 0x3800, v2
	s_waitcnt lgkmcnt(0)
	v_mfma_f32_16x16x32_bf16 v[76:79], v[208:211], v[60:63], v[76:79]
	v_add_u32_e32 v138, 0x4000, v2
	v_pk_mul_f32 v[66:67], v[66:67], v[178:179] op_sel_hi:[1,0]
	v_pk_mul_f32 v[64:65], v[64:65], v[178:179] op_sel_hi:[1,0]
	v_mfma_f32_16x16x32_bf16 v[80:83], v[208:211], v[44:47], v[80:83]
	v_pk_mul_f32 v[50:51], v[50:51], v[150:151] op_sel_hi:[1,0]
	v_pk_mul_f32 v[48:49], v[48:49], v[150:151] op_sel_hi:[1,0]
	v_mfma_f32_16x16x32_bf16 v[72:75], v[212:215], v[60:63], v[72:75]
	v_add_u32_e32 v2, 0x4800, v2
	v_pk_mul_f32 v[40:41], v[52:53], v[150:151] op_sel_hi:[1,0]
	v_cvt_pk_bf16_f32 v52, v144, v145
	v_mfma_f32_16x16x32_bf16 v[84:87], v[212:215], v[44:47], v[84:87]
	v_cvt_pk_bf16_f32 v55, v142, v143
	v_cvt_pk_bf16_f32 v71, v176, v177
	v_mfma_f32_16x16x32_bf16 v[64:67], v[216:219], v[60:63], v[64:67]
	v_cvt_pk_bf16_f32 v53, v148, v149
	v_fmac_f32_e32 v140, v174, v178
	v_mov_b32_e32 v173, v141
	v_mfma_f32_16x16x32_bf16 v[48:51], v[216:219], v[44:47], v[48:51]
	v_mov_b32_e32 v175, v0
	v_mov_b32_e32 v174, v140
	v_mfma_f32_16x16x32_bf16 v[142:145], v[220:223], v[60:63], v[56:59]
	s_movk_i32 s58, 0x420
	v_mfma_f32_16x16x32_bf16 v[134:137], v[220:223], v[44:47], v[40:43]
	v_mov_b32_e32 v127, v151
	v_mfma_f32_16x16x32_bf16 v[60:63], v[224:227], v[68:71], v[72:75]
	s_nop 2
	ds_read2_b64 v[40:43], v3 offset0:136 offset1:140
	ds_read2_b64 v[72:75], v2 offset0:184 offset1:188
	v_mfma_f32_16x16x32_bf16 v[64:67], v[228:231], v[68:71], v[64:67]
	v_mfma_f32_16x16x32_bf16 v[48:51], v[228:231], v[52:55], v[48:51]
	s_waitcnt lgkmcnt(1)
	v_mfma_f32_16x16x32_bf16 v[56:59], v[40:43], v[68:71], v[76:79]
	v_mfma_f32_16x16x32_bf16 v[40:43], v[40:43], v[52:55], v[80:83]
	v_mfma_f32_16x16x32_bf16 v[44:47], v[224:227], v[52:55], v[84:87]
	s_waitcnt lgkmcnt(0)
	v_mfma_f32_16x16x32_bf16 v[68:71], v[72:75], v[68:71], v[142:145]
	v_mfma_f32_16x16x32_bf16 v[52:55], v[72:75], v[52:55], v[134:137]
	s_add_i32 s66, s66, 64
	s_cmp_eq_u32 s63, s67
	s_cbranch_scc0 .LBB0_504
	s_branch .LBB0_505

; template <bool MLA>
; __device__ __forceinline__ void attn_phase(const Args& a, LAS unsigned char* lds) {
;     ...
;             for (int g = 0; g < 2; ++g) {
;                 f32x4 sv[4];
; #pragma unroll
;                 for (int sub = 0; sub < 4; ++sub) sv[sub] = s[g][sub] * scale;
;                 if (!MLA) {
; #pragma unroll
;                     for (int sub = 0; sub < 4; ++sub)
; #pragma unroll
;                         for (int jj = 0; jj < 4; ++jj) sv[sub][jj] += biasT[head * 256 + 191 + qi[g] - (kt * 64 + sub * 16 + quad * 4 + jj)];
;                 }
;                 if (need_mask) {
; #pragma unroll
;                     for (int sub = 0; sub < 4; ++sub)
; #pragma unroll
;                         for (int jj = 0; jj < 4; ++jj) if (kt * 64 + sub * 16 + quad * 4 + jj >= nkw) sv[sub][jj] = -INFINITY;
;                 }
;                 float mx = -INFINITY;
; #pragma unroll
;                 for (int sub = 0; sub < 4; ++sub) mx = fmaxf(fmaxf(fmaxf(mx, sv[sub][0]), fmaxf(sv[sub][1], sv[sub][2])), sv[sub][3]);
;                 mx = fmaxf(mx, __shfl_xor(mx, 16)); mx = fmaxf(mx, __shfl_xor(mx, 32));
.LBB0_865:
	v_add_u32_e32 v88, s56, v103
	v_add_u32_e32 v82, 0xbf, v88
	v_readlane_b32 s0, v252, 16
	v_add_u32_e32 v84, 0xbe, v88
	v_ashrrev_i32_e32 v83, 31, v82
	v_readlane_b32 s1, v252, 17
	v_ashrrev_i32_e32 v85, 31, v84
	v_add_u32_e32 v86, 0xbc, v88
	v_lshl_add_u64 v[82:83], v[82:83], 2, s[0:1]
	v_lshl_add_u64 v[84:85], v[84:85], 2, s[0:1]
	global_load_dword v82, v[82:83], off
	v_ashrrev_i32_e32 v87, 31, v86
	global_load_dword v83, v[84:85], off
	v_add_u32_e32 v84, 0xbd, v88
	v_ashrrev_i32_e32 v85, 31, v84
	v_lshl_add_u64 v[84:85], v[84:85], 2, s[0:1]
	v_lshl_add_u64 v[86:87], v[86:87], 2, s[0:1]
	global_load_dword v84, v[84:85], off
	s_andn2_b64 vcc, exec, s[46:47]
	global_load_dword v85, v[86:87], off
	v_add_u32_e32 v86, 0xaf, v88
	v_ashrrev_i32_e32 v87, 31, v86
	v_lshl_add_u64 v[86:87], v[86:87], 2, s[0:1]
	global_load_dword v120, v[86:87], off
	v_add_u32_e32 v86, 0xae, v88
	v_ashrrev_i32_e32 v87, 31, v86
	v_lshl_add_u64 v[86:87], v[86:87], 2, s[0:1]
	global_load_dword v121, v[86:87], off
	v_add_u32_e32 v86, 0xad, v88
	v_ashrrev_i32_e32 v87, 31, v86
	v_lshl_add_u64 v[86:87], v[86:87], 2, s[0:1]
	global_load_dword v160, v[86:87], off
	v_add_u32_e32 v86, 0xac, v88
	v_ashrrev_i32_e32 v87, 31, v86
	v_lshl_add_u64 v[86:87], v[86:87], 2, s[0:1]
	global_load_dword v161, v[86:87], off
	v_add_u32_e32 v86, 0x9f, v88
	v_ashrrev_i32_e32 v87, 31, v86
	v_lshl_add_u64 v[86:87], v[86:87], 2, s[0:1]
	global_load_dword v162, v[86:87], off
	v_add_u32_e32 v86, 0x9e, v88
	v_ashrrev_i32_e32 v87, 31, v86
	v_lshl_add_u64 v[86:87], v[86:87], 2, s[0:1]
	global_load_dword v163, v[86:87], off
	v_add_u32_e32 v86, 0x9d, v88
	v_ashrrev_i32_e32 v87, 31, v86
	v_lshl_add_u64 v[86:87], v[86:87], 2, s[0:1]
	global_load_dword v164, v[86:87], off
	v_add_u32_e32 v86, 0x9c, v88
	v_ashrrev_i32_e32 v87, 31, v86
	v_lshl_add_u64 v[86:87], v[86:87], 2, s[0:1]
	global_load_dword v165, v[86:87], off
	v_add_u32_e32 v86, 0x8f, v88
	v_ashrrev_i32_e32 v87, 31, v86
	v_lshl_add_u64 v[86:87], v[86:87], 2, s[0:1]
	global_load_dword v166, v[86:87], off
	v_add_u32_e32 v86, 0x8d, v88
	v_ashrrev_i32_e32 v87, 31, v86
	v_lshl_add_u64 v[86:87], v[86:87], 2, s[0:1]
	global_load_dword v168, v[86:87], off
	v_add_u32_e32 v86, 0x8c, v88
	v_ashrrev_i32_e32 v87, 31, v86
	v_lshl_add_u64 v[86:87], v[86:87], 2, s[0:1]
	global_load_dword v169, v[86:87], off
	v_add_u32_e32 v86, 0x8e, v88
	v_ashrrev_i32_e32 v87, 31, v86
	v_lshl_add_u64 v[86:87], v[86:87], 2, s[0:1]
	global_load_dword v167, v[86:87], off
	v_max3_f32 v86, v114, v117, v116
	v_max3_f32 v87, v80, v79, v78
	v_max3_f32 v86, v86, v110, v113
	v_max3_f32 v87, v87, v74, v77
	v_max3_f32 v86, v86, v115, v112
	v_max3_f32 v87, v87, v81, v76
	s_mov_b32 s0, 0xff800000
	v_max_f32_e32 v86, v86, v111
	v_max3_f32 v86, v86, v87, v75
	ds_bpermute_b32 v87, v132, v86
	s_mov_b32 s0, 0x3e38aa3b
	s_waitcnt lgkmcnt(0)
	v_max_f32_e32 v118, v86, v87
	ds_bpermute_b32 v119, v133, v118
	s_waitcnt vmcnt(14)
	v_pk_fma_f32 v[88:89], v[62:63], s[0:1], v[82:83] op_sel_hi:[1,0,1]
	s_waitcnt vmcnt(12)
	v_pk_fma_f32 v[86:87], v[64:65], s[0:1], v[84:85] op_sel_hi:[1,0,1]
	s_waitcnt vmcnt(10)
	v_pk_fma_f32 v[84:85], v[66:67], s[0:1], v[120:121] op_sel_hi:[1,0,1]
	s_waitcnt vmcnt(8)
	v_pk_fma_f32 v[82:83], v[68:69], s[0:1], v[160:161] op_sel_hi:[1,0,1]
	s_waitcnt vmcnt(6)
	v_pk_fma_f32 v[70:71], v[70:71], s[0:1], v[162:163] op_sel_hi:[1,0,1]
	s_waitcnt vmcnt(4)
	v_pk_fma_f32 v[68:69], v[72:73], s[0:1], v[164:165] op_sel_hi:[1,0,1]
	s_waitcnt vmcnt(1)
	v_pk_fma_f32 v[66:67], v[60:61], s[0:1], v[168:169] op_sel_hi:[1,0,1]
	s_waitcnt vmcnt(0)
	v_pk_fma_f32 v[72:73], v[58:59], s[0:1], v[166:167] op_sel_hi:[1,0,1]
	s_cbranch_vccnz .LBB0_867
	v_cmp_gt_i32_e64 s[26:27], s53, v158
	v_cmp_gt_i32_e64 s[28:29], s53, v159
	v_cmp_gt_i32_e64 s[24:25], s53, v157
	s_or_b64 s[26:27], s[28:29], s[26:27]
	v_cmp_gt_i32_e64 s[22:23], s53, v156
	s_or_b64 s[24:25], s[26:27], s[24:25]
	v_cmp_gt_i32_e64 s[20:21], s53, v155
	s_or_b64 s[22:23], s[24:25], s[22:23]
	v_cmp_gt_i32_e64 s[18:19], s53, v154
	s_or_b64 s[20:21], s[22:23], s[20:21]
	v_cmp_gt_i32_e64 s[16:17], s53, v153
	s_or_b64 s[18:19], s[20:21], s[18:19]
	v_cmp_gt_i32_e64 s[14:15], s53, v152
	s_or_b64 s[16:17], s[18:19], s[16:17]
	v_cmp_gt_i32_e64 s[12:13], s53, v151
	s_or_b64 s[14:15], s[16:17], s[14:15]
	v_cmp_gt_i32_e64 s[10:11], s53, v150
	s_or_b64 s[12:13], s[14:15], s[12:13]
	v_cmp_gt_i32_e64 s[8:9], s53, v149
	s_or_b64 s[10:11], s[12:13], s[10:11]
	v_cmp_gt_i32_e64 s[6:7], s53, v148
	s_or_b64 s[8:9], s[10:11], s[8:9]
	v_cmp_gt_i32_e64 s[4:5], s53, v147
	s_or_b64 s[6:7], s[8:9], s[6:7]
	v_cmp_gt_i32_e64 s[2:3], s53, v146
	s_or_b64 s[4:5], s[6:7], s[4:5]
	v_cmp_gt_i32_e64 s[0:1], s53, v145
	s_or_b64 s[2:3], s[4:5], s[2:3]
	v_cmp_gt_i32_e32 vcc, s53, v144
	s_or_b64 s[0:1], s[2:3], s[0:1]
	s_or_b64 vcc, s[0:1], vcc
	v_cndmask_b32_e64 v67, v245, v67, s[28:29]
	v_cndmask_b32_e64 v66, v245, v66, s[26:27]
	v_cndmask_b32_e64 v73, v245, v73, s[24:25]
	v_cndmask_b32_e64 v72, v245, v72, s[22:23]
	v_cndmask_b32_e64 v69, v245, v69, s[20:21]
	v_cndmask_b32_e64 v68, v245, v68, s[18:19]
	v_cndmask_b32_e64 v71, v245, v71, s[16:17]
	v_cndmask_b32_e64 v70, v245, v70, s[14:15]
	v_cndmask_b32_e64 v83, v245, v83, s[12:13]
	v_cndmask_b32_e64 v82, v245, v82, s[10:11]
	v_cndmask_b32_e64 v85, v245, v85, s[8:9]
	v_cndmask_b32_e64 v84, v245, v84, s[6:7]
	v_cndmask_b32_e64 v87, v245, v87, s[4:5]
	v_cndmask_b32_e64 v86, v245, v86, s[2:3]
	v_cndmask_b32_e64 v89, v245, v89, s[0:1]
	v_cndmask_b32_e32 v88, v245, v88, vcc
; #define LAS __attribute__((address_space(3)))
; template <bool MLA>
; __device__ __forceinline__ void attn_phase(const Args& a, LAS unsigned char* lds) {
;     ...
;                 float mx = -INFINITY;
; #pragma unroll
;                 for (int sub = 0; sub < 4; ++sub) mx = fmaxf(fmaxf(fmaxf(mx, sv[sub][0]), fmaxf(sv[sub][1], sv[sub][2])), sv[sub][3]);
;                 mx = fmaxf(mx, __shfl_xor(mx, 16)); mx = fmaxf(mx, __shfl_xor(mx, 32));
;                 const float mn = fmaxf(m[g], mx), alpha = __builtin_amdgcn_exp2f(m[g] - mn); m[g] = mn;
;                 f32x4 ps4 = (f32x4){0.f, 0.f, 0.f, 0.f};
; #pragma unroll
;                 for (int sub = 0; sub < 4; ++sub) {
;                     const f32x4 d = sv[sub] - mn;
;                     const f32x4 pe = (f32x4){__builtin_amdgcn_exp2f(d[0]), __builtin_amdgcn_exp2f(d[1]), __builtin_amdgcn_exp2f(d[2]), __builtin_amdgcn_exp2f(d[3])};
;                     s[g][sub] = pe; ps4 += pe;
;                 }
;                 lsum[g] = lsum[g] * alpha + ((ps4[0] + ps4[1]) + (ps4[2] + ps4[3]));
; #pragma unroll
;                 for (int et = 0; et < 4; ++et) O[g][et] *= alpha;
; #pragma unroll
;                 for (int s2 = 0; s2 < 2; ++s2) {
;                     const unsigned a0 = pk2(s[g][2 * s2][0], s[g][2 * s2][1]), a1 = pk2(s[g][2 * s2][2], s[g][2 * s2][3]), a2 = pk2(s[g][2 * s2 + 1][0], s[g][2 * s2 + 1][1]), a3 = pk2(s[g][2 * s2 + 1][2], s[g][2 * s2 + 1][3]);
;                     const u32x4 pu = (u32x4){a0, a1, a2, a3}; pf[g][s2] = *(const bf16x8*)&pu;
;                 }
;             }
; #pragma unroll
;             for (int s2 = 0; s2 < 2; ++s2)
; #pragma unroll
;                 for (int et = 0; et < 4; ++et) {
;                     const LAS bf16_t* vp = VTs + (et * 16 + r) * 68 + s2 * 32 + quad * 4;
;                     const u32x2 v0 = *(const LAS u32x2*)vp, v1 = *(const LAS u32x2*)(vp + 16);
;                     const u32x4 vu = (u32x4){v0.x, v0.y, v1.x, v1.y};
;                     O[0][et] = __builtin_amdgcn_mfma_f32_16x16x32_bf16(*(const bf16x8*)&vu, pf[0][s2], O[0][et], 0, 0, 0);
;                     O[1][et] = __builtin_amdgcn_mfma_f32_16x16x32_bf16(*(const bf16x8*)&vu, pf[1][s2], O[1][et], 0, 0, 0);
;                 }
.LBB0_867:
	s_waitcnt lgkmcnt(0)
	v_max3_f32 v118, v143, v118, v119
	v_sub_f32_e32 v60, v117, v118
	v_sub_f32_e32 v61, v116, v118
	v_sub_f32_e32 v58, v115, v118
	v_sub_f32_e32 v59, v114, v118
	v_exp_f32_e32 v114, v61
	v_exp_f32_e32 v115, v60
	v_sub_f32_e32 v64, v110, v118
	v_sub_f32_e32 v65, v113, v118
	v_sub_f32_e32 v110, v112, v118
	v_sub_f32_e32 v63, v111, v118
	v_exp_f32_e32 v110, v110
	v_exp_f32_e32 v111, v65
	v_exp_f32_e32 v112, v64
	v_sub_f32_e32 v64, v80, v118
	v_sub_f32_e32 v65, v79, v118
	v_sub_f32_e32 v78, v78, v118
	v_sub_f32_e32 v62, v143, v118
	v_exp_f32_e32 v78, v78
	v_exp_f32_e32 v79, v65
	v_exp_f32_e32 v80, v64
	v_sub_f32_e32 v64, v74, v118
	v_sub_f32_e32 v65, v77, v118
	v_sub_f32_e32 v74, v76, v118
	v_exp_f32_e32 v76, v74
	v_exp_f32_e32 v77, v65
	v_exp_f32_e32 v144, v62
	v_exp_f32_e32 v116, v59
	v_exp_f32_e32 v117, v58
	v_pk_add_f32 v[58:59], v[114:115], 0 op_sel_hi:[1,0]
	v_exp_f32_e32 v113, v63
	v_pk_add_f32 v[58:59], v[110:111], v[58:59]
	v_sub_f32_e32 v63, v81, v118
	v_pk_add_f32 v[58:59], v[78:79], v[58:59]
	v_exp_f32_e32 v81, v63
	v_sub_f32_e32 v63, v75, v118
	v_exp_f32_e32 v120, v64
	v_pk_add_f32 v[58:59], v[76:77], v[58:59]
	v_pk_mul_f32 v[64:65], v[44:45], v[144:145] op_sel_hi:[1,0]
	v_pk_mul_f32 v[44:45], v[56:57], v[144:145] op_sel_hi:[1,0]
	v_cvt_pk_bf16_f32 v56, v76, v77
	v_max3_f32 v75, v86, v89, v88
	v_max3_f32 v76, v68, v71, v70
	v_max3_f32 v75, v75, v82, v85
	v_max3_f32 v76, v76, v66, v73
	v_max3_f32 v75, v75, v87, v84
	v_max3_f32 v76, v76, v69, v72
	s_mov_b32 s0, 0xff800000
	v_max_f32_e32 v75, v75, v83
	v_max3_f32 v75, v75, v76, v67
	ds_bpermute_b32 v76, v132, v75
	v_exp_f32_e32 v121, v63
	v_pk_add_f32 v[60:61], v[116:117], 0 op_sel_hi:[1,0]
	v_pk_mul_f32 v[62:63], v[42:43], v[144:145] op_sel_hi:[1,0]
	v_pk_add_f32 v[60:61], v[112:113], v[60:61]
	s_waitcnt lgkmcnt(0)
	v_max_f32_e32 v75, v75, v76
	ds_bpermute_b32 v76, v133, v75
	v_pk_mul_f32 v[42:43], v[54:55], v[144:145] op_sel_hi:[1,0]
	v_cvt_pk_bf16_f32 v54, v78, v79
	v_pk_add_f32 v[60:61], v[80:81], v[60:61]
	v_cvt_pk_bf16_f32 v55, v80, v81
	s_waitcnt lgkmcnt(0)
	v_max3_f32 v75, v141, v75, v76
	v_sub_f32_e32 v76, v87, v75
	v_sub_f32_e32 v77, v86, v75
	v_sub_f32_e32 v78, v89, v75
	v_sub_f32_e32 v79, v88, v75
	v_exp_f32_e32 v80, v79
	v_exp_f32_e32 v81, v78
	v_exp_f32_e32 v86, v77
	v_exp_f32_e32 v87, v76
	v_sub_f32_e32 v88, v83, v75
	v_sub_f32_e32 v89, v82, v75
	v_sub_f32_e32 v83, v85, v75
	v_sub_f32_e32 v82, v84, v75
	v_pk_add_f32 v[60:61], v[120:121], v[60:61]
	v_exp_f32_e32 v82, v82
	v_exp_f32_e32 v83, v83
	v_exp_f32_e32 v84, v89
	v_exp_f32_e32 v85, v88
	v_sub_f32_e32 v69, v69, v75
	v_sub_f32_e32 v68, v68, v75
	v_sub_f32_e32 v71, v71, v75
	v_sub_f32_e32 v70, v70, v75
	v_add_f32_e32 v58, v58, v59
	v_add_f32_e32 v59, v60, v61
	v_pk_mul_f32 v[60:61], v[48:49], v[144:145] op_sel_hi:[1,0]
	v_cvt_pk_bf16_f32 v48, v110, v111
	v_exp_f32_e32 v88, v70
	v_exp_f32_e32 v89, v71
	v_exp_f32_e32 v110, v68
	v_exp_f32_e32 v111, v69
	v_sub_f32_e32 v67, v67, v75
	v_sub_f32_e32 v66, v66, v75
	v_sub_f32_e32 v73, v73, v75
	v_sub_f32_e32 v72, v72, v75
	v_cvt_pk_bf16_f32 v49, v112, v113
	v_exp_f32_e32 v72, v72
	v_exp_f32_e32 v73, v73
	v_exp_f32_e32 v112, v66
	v_exp_f32_e32 v113, v67
	v_pk_add_f32 v[76:77], v[80:81], 0 op_sel_hi:[1,0]
	v_pk_add_f32 v[78:79], v[86:87], 0 op_sel_hi:[1,0]
	v_pk_add_f32 v[76:77], v[82:83], v[76:77]
	v_pk_add_f32 v[78:79], v[84:85], v[78:79]
	v_add_f32_e32 v74, v58, v59
	v_pk_mul_f32 v[58:59], v[46:47], v[144:145] op_sel_hi:[1,0]
	v_cvt_pk_bf16_f32 v46, v114, v115
	v_sub_f32_e32 v114, v141, v75
	v_pk_add_f32 v[68:69], v[88:89], v[76:77]
	v_pk_add_f32 v[70:71], v[110:111], v[78:79]
	v_pk_add_f32 v[68:69], v[72:73], v[68:69]
	v_pk_add_f32 v[66:67], v[112:113], v[70:71]
	v_exp_f32_e32 v114, v114
	v_pk_mov_b32 v[70:71], v[68:69], v[66:67] op_sel:[1,0]
	v_mov_b32_e32 v69, v67
	v_pk_add_f32 v[66:67], v[70:71], v[68:69]
	v_pk_mul_f32 v[70:71], v[28:29], v[114:115] op_sel_hi:[1,0]
	v_add_f32_e32 v66, v66, v67
	v_add3_u32 v67, s59, v94, v135
	v_pk_mul_f32 v[28:29], v[40:41], v[114:115] op_sel_hi:[1,0]
	v_cvt_pk_bf16_f32 v40, v72, v73
	v_add_u32_e32 v72, 0xb000, v67
	v_pk_mul_f32 v[78:79], v[32:33], v[114:115] op_sel_hi:[1,0]
	v_pk_mul_f32 v[76:77], v[30:31], v[114:115] op_sel_hi:[1,0]
	v_cvt_pk_bf16_f32 v30, v80, v81
	v_cvt_pk_bf16_f32 v32, v82, v83
	ds_read2_b64 v[80:83], v72 offset0:128 offset1:132
	v_cvt_pk_bf16_f32 v47, v116, v117
	v_pk_mul_f32 v[68:69], v[26:27], v[114:115] op_sel_hi:[1,0]
	v_cvt_pk_bf16_f32 v31, v86, v87
	v_cvt_pk_bf16_f32 v33, v84, v85
	v_add_u32_e32 v73, 0xb800, v67
	s_waitcnt lgkmcnt(0)
	v_mfma_f32_16x16x32_bf16 v[62:65], v[80:83], v[46:49], v[62:65]
	v_mul_f32_e64 v26, v38, v114
	v_mul_f32_e64 v27, v39, v114
	v_cvt_pk_bf16_f32 v38, v88, v89
	v_add_u32_e32 v88, 0xc000, v67
	v_mfma_f32_16x16x32_bf16 v[68:71], v[80:83], v[30:33], v[68:71]
	ds_read2_b64 v[80:83], v73 offset0:144 offset1:148
	v_pk_mul_f32 v[52:53], v[52:53], v[144:145] op_sel_hi:[1,0]
	v_pk_mul_f32 v[50:51], v[50:51], v[144:145] op_sel_hi:[1,0]
	s_waitcnt lgkmcnt(0)
	v_mfma_f32_16x16x32_bf16 v[58:61], v[80:83], v[46:49], v[58:61]
	v_mul_f32_e64 v36, v36, v114
	v_mul_f32_e64 v37, v37, v114
	v_pk_mul_f32 v[34:35], v[34:35], v[114:115] op_sel_hi:[1,0]
	v_add_u32_e32 v67, 0xc800, v67
	v_mfma_f32_16x16x32_bf16 v[76:79], v[80:83], v[30:33], v[76:79]
	ds_read2_b64 v[80:83], v88 offset0:160 offset1:164
	v_cvt_pk_bf16_f32 v57, v120, v121
	v_cvt_pk_bf16_f32 v39, v110, v111
	s_waitcnt lgkmcnt(0)
	v_mfma_f32_16x16x32_bf16 v[50:53], v[80:83], v[46:49], v[50:53]
	v_cvt_pk_bf16_f32 v41, v112, v113
	s_mov_b64 s[0:1], 0x8000
	s_add_i32 s57, s57, 1
	v_mfma_f32_16x16x32_bf16 v[34:37], v[80:83], v[30:33], v[34:37]
	ds_read2_b64 v[80:83], v67 offset0:176 offset1:180
	v_lshl_add_u64 v[108:109], v[108:109], 0, s[0:1]
	s_add_i32 s0, s52, s57
	s_waitcnt lgkmcnt(0)
	v_mfma_f32_16x16x32_bf16 v[84:87], v[80:83], v[46:49], v[42:45]
	s_add_i32 s43, s43, 64
	s_add_i32 s0, s0, -1
	s_sub_i32 s56, s56, 64
	v_mfma_f32_16x16x32_bf16 v[80:83], v[80:83], v[30:33], v[26:29]
	ds_read2_b64 v[30:33], v73 offset0:152 offset1:156
	s_add_i32 s58, s58, 1
	v_fmac_f32_e32 v74, v142, v144
	s_waitcnt lgkmcnt(0)
	v_mfma_f32_16x16x32_bf16 v[46:49], v[30:33], v[54:57], v[58:61]
	s_nop 2
	ds_read2_b64 v[58:61], v88 offset0:168 offset1:172
	ds_read2_b64 v[26:29], v72 offset0:136 offset1:140
	v_fmac_f32_e32 v66, v140, v114
	s_waitcnt lgkmcnt(1)
	v_mfma_f32_16x16x32_bf16 v[50:53], v[58:61], v[54:57], v[50:53]
	s_cmp_gt_i32 s0, 1
	v_mfma_f32_16x16x32_bf16 v[34:37], v[58:61], v[38:41], v[34:37]
	ds_read2_b64 v[58:61], v67 offset0:184 offset1:188
	s_waitcnt lgkmcnt(1)
	v_mfma_f32_16x16x32_bf16 v[42:45], v[26:29], v[54:57], v[62:65]
	v_mfma_f32_16x16x32_bf16 v[26:29], v[26:29], v[38:41], v[68:71]
	v_mfma_f32_16x16x32_bf16 v[30:33], v[30:33], v[38:41], v[76:79]
	s_waitcnt lgkmcnt(0)
	v_mfma_f32_16x16x32_bf16 v[54:57], v[58:61], v[54:57], v[84:87]
	v_mfma_f32_16x16x32_bf16 v[38:41], v[58:61], v[38:41], v[80:83]
	s_cbranch_scc1 .LBB0_882
; template <bool MLA>
; __device__ __forceinline__ void attn_phase(const Args& a, LAS unsigned char* lds) {
;     ...
;                 const float mn = fmaxf(m[g], mx), alpha = __builtin_amdgcn_exp2f(m[g] - mn); m[g] = mn;
;                 f32x4 ps4 = (f32x4){0.f, 0.f, 0.f, 0.f};
; #pragma unroll
;                 for (int sub = 0; sub < 4; ++sub) {
;                     const f32x4 d = sv[sub] - mn;
;                     const f32x4 pe = (f32x4){__builtin_amdgcn_exp2f(d[0]), __builtin_amdgcn_exp2f(d[1]), __builtin_amdgcn_exp2f(d[2]), __builtin_amdgcn_exp2f(d[3])};
;                     s[g][sub] = pe; ps4 += pe;
;                 }
;                 lsum[g] = lsum[g] * alpha + ((ps4[0] + ps4[1]) + (ps4[2] + ps4[3]));
	v_mov_b32_e32 v141, v75
	v_mov_b32_e32 v143, v118
	v_mov_b32_e32 v140, v66
	v_mov_b32_e32 v142, v74
	s_branch .LBB0_859
